# attention items fetch the next queue index during their epilogue (returned atomic hidden behind the gate loads)
# speedup vs baseline: 1.0063x; 1.0012x over previous
.LBB0_870:
	s_or_b64 exec, exec, s[54:55]
	s_mov_b64 s[40:41], exec
	s_and_b64 exec, exec, s[92:93]
	s_cbranch_execz .Lipf_skip
	v_mov_b32_e32 v252, 1
	global_atomic_add v251, v3, v252, s[44:45] sc0
.Lipf_skip:
	s_mov_b64 exec, s[40:41]
	v_readlane_b32 s12, v235, 2
	v_readlane_b32 s13, v235, 3
	v_readlane_b32 s0, v236, 44
	v_readlane_b32 s1, v236, 45
	v_lshlrev_b32_e32 v32, 7, v181
	v_lshl_add_u32 v32, v187, 1, v32
	v_mul_lo_u32 v33, v166, s78
	v_lshl_add_u32 v35, v166, 11, v32
	v_add_u32_e32 v33, v33, v32
	v_add_u32_e32 v36, 0x8000, v35
	v_add_u32_e32 v34, 0x1b000, v33
	s_add_u32 s0, s0, 0x1640
	s_addc_u32 s1, s1, 0
	s_nop 1
	global_load_dwordx2 v[100:101], v33, s[0:1]
	global_load_dwordx2 v[102:103], v33, s[0:1] offset:32
	global_load_dwordx2 v[104:105], v33, s[0:1] offset:64
	global_load_dwordx2 v[106:107], v33, s[0:1] offset:96
	global_load_dwordx2 v[108:109], v34, s[0:1]
	global_load_dwordx2 v[110:111], v34, s[0:1] offset:32
	global_load_dwordx2 v[112:113], v34, s[0:1] offset:64
	global_load_dwordx2 v[114:115], v34, s[0:1] offset:96
	v_mov_b32_e32 v38, v165
	s_nop 1
	v_permlane16_swap_b32_e32 v165, v38
	s_nop 1
	v_add_f32_e32 v165, v165, v38
	s_nop 0
	v_mov_b32_e32 v38, v165
	s_nop 1
	v_permlane32_swap_b32_e32 v165, v38
	s_nop 1
	v_add_f32_e32 v165, v165, v38
	v_mov_b32_e32 v40, v164
	s_nop 1
	v_permlane16_swap_b32_e32 v164, v40
	s_nop 1
	v_add_f32_e32 v164, v164, v40
	s_nop 0
	v_mov_b32_e32 v40, v164
	s_nop 1
	v_permlane32_swap_b32_e32 v164, v40
	s_nop 1
	v_add_f32_e32 v164, v164, v40
	s_nop 0
	v_div_scale_f32 v44, s[40:41], v165, v165, 1.0
	v_rcp_f32_e32 v45, v44
	s_nop 0
	v_fma_f32 v46, -v44, v45, 1.0
	v_fmac_f32_e32 v45, v46, v45
	v_div_scale_f32 v46, vcc, 1.0, v165, 1.0
	v_mul_f32_e32 v47, v46, v45
	v_fma_f32 v48, -v44, v47, v46
	v_fmac_f32_e32 v47, v48, v45
	v_fma_f32 v44, -v44, v47, v46
	v_div_fmas_f32 v44, v44, v45, v47
	v_div_fixup_f32 v41, v44, v165, 1.0
	s_nop 0
	v_div_scale_f32 v44, s[40:41], v164, v164, 1.0
	v_rcp_f32_e32 v45, v44
	s_nop 0
	v_fma_f32 v46, -v44, v45, 1.0
	v_fmac_f32_e32 v45, v46, v45
	v_div_scale_f32 v46, vcc, 1.0, v164, 1.0
	v_mul_f32_e32 v47, v46, v45
	v_fma_f32 v48, -v44, v47, v46
	v_fmac_f32_e32 v47, v48, v45
	v_fma_f32 v44, -v44, v47, v46
	v_div_fmas_f32 v44, v44, v45, v47
	v_div_fixup_f32 v42, v44, v164, 1.0
	s_waitcnt vmcnt(0)
	v_readfirstlane_b32 s40, v251
	s_nop 3
	s_add_u32 s40, s40, 1
	v_writelane_b32 v233, s40, 58
	v_lshlrev_b32_e32 v44, 16, v100
	v_and_b32_e32 v45, 0xffff0000, v100
	v_lshlrev_b32_e32 v46, 16, v101
	v_and_b32_e32 v47, 0xffff0000, v101
	v_mul_f32_e32 v48, 0xbfb8aa3b, v44
	v_mul_f32_e32 v49, 0xbfb8aa3b, v45
	v_mul_f32_e32 v50, 0xbfb8aa3b, v46
	v_mul_f32_e32 v51, 0xbfb8aa3b, v47
	v_exp_f32_e32 v48, v48
	v_exp_f32_e32 v49, v49
	v_exp_f32_e32 v50, v50
	v_exp_f32_e32 v51, v51
	v_mul_f32_e32 v52, v96, v41
	v_mul_f32_e32 v53, v97, v41
	v_mul_f32_e32 v54, v98, v41
	v_mul_f32_e32 v55, v99, v41
	v_add_f32_e32 v48, 1.0, v48
	v_add_f32_e32 v49, 1.0, v49
	v_add_f32_e32 v50, 1.0, v50
	v_add_f32_e32 v51, 1.0, v51
	v_rcp_f32_e32 v48, v48
	v_rcp_f32_e32 v49, v49
	v_rcp_f32_e32 v50, v50
	v_rcp_f32_e32 v51, v51
	s_nop 0
	v_mul_f32_e32 v48, v48, v44
	v_mul_f32_e32 v49, v49, v45
	v_mul_f32_e32 v50, v50, v46
	v_mul_f32_e32 v51, v51, v47
	v_mul_f32_e32 v52, v52, v48
	v_mul_f32_e32 v53, v53, v49
	v_mul_f32_e32 v54, v54, v50
	v_mul_f32_e32 v55, v55, v51
	v_cvt_pk_bf16_f32 v56, v52, v53
	v_cvt_pk_bf16_f32 v57, v54, v55
	global_store_dwordx2 v35, v[56:57], s[12:13] offset:1024
	v_lshlrev_b32_e32 v44, 16, v102
	v_and_b32_e32 v45, 0xffff0000, v102
	v_lshlrev_b32_e32 v46, 16, v103
	v_and_b32_e32 v47, 0xffff0000, v103
	v_mul_f32_e32 v48, 0xbfb8aa3b, v44
	v_mul_f32_e32 v49, 0xbfb8aa3b, v45
	v_mul_f32_e32 v50, 0xbfb8aa3b, v46
	v_mul_f32_e32 v51, 0xbfb8aa3b, v47
	v_exp_f32_e32 v48, v48
	v_exp_f32_e32 v49, v49
	v_exp_f32_e32 v50, v50
	v_exp_f32_e32 v51, v51
	v_mul_f32_e32 v52, v28, v41
	v_mul_f32_e32 v53, v29, v41
	v_mul_f32_e32 v54, v30, v41
	v_mul_f32_e32 v55, v31, v41
	v_add_f32_e32 v48, 1.0, v48
	v_add_f32_e32 v49, 1.0, v49
	v_add_f32_e32 v50, 1.0, v50
	v_add_f32_e32 v51, 1.0, v51
	v_rcp_f32_e32 v48, v48
	v_rcp_f32_e32 v49, v49
	v_rcp_f32_e32 v50, v50
	v_rcp_f32_e32 v51, v51
	s_nop 0
	v_mul_f32_e32 v48, v48, v44
	v_mul_f32_e32 v49, v49, v45
	v_mul_f32_e32 v50, v50, v46
	v_mul_f32_e32 v51, v51, v47
	v_mul_f32_e32 v52, v52, v48
	v_mul_f32_e32 v53, v53, v49
	v_mul_f32_e32 v54, v54, v50
	v_mul_f32_e32 v55, v55, v51
	v_cvt_pk_bf16_f32 v56, v52, v53
	v_cvt_pk_bf16_f32 v57, v54, v55
	global_store_dwordx2 v35, v[56:57], s[12:13] offset:1056
	v_lshlrev_b32_e32 v44, 16, v104
	v_and_b32_e32 v45, 0xffff0000, v104
	v_lshlrev_b32_e32 v46, 16, v105
	v_and_b32_e32 v47, 0xffff0000, v105
	v_mul_f32_e32 v48, 0xbfb8aa3b, v44
	v_mul_f32_e32 v49, 0xbfb8aa3b, v45
	v_mul_f32_e32 v50, 0xbfb8aa3b, v46
	v_mul_f32_e32 v51, 0xbfb8aa3b, v47
	v_exp_f32_e32 v48, v48
	v_exp_f32_e32 v49, v49
	v_exp_f32_e32 v50, v50
	v_exp_f32_e32 v51, v51
	v_mul_f32_e32 v52, v24, v41
	v_mul_f32_e32 v53, v25, v41
	v_mul_f32_e32 v54, v26, v41
	v_mul_f32_e32 v55, v27, v41
	v_add_f32_e32 v48, 1.0, v48
	v_add_f32_e32 v49, 1.0, v49
	v_add_f32_e32 v50, 1.0, v50
	v_add_f32_e32 v51, 1.0, v51
	v_rcp_f32_e32 v48, v48
	v_rcp_f32_e32 v49, v49
	v_rcp_f32_e32 v50, v50
	v_rcp_f32_e32 v51, v51
	s_nop 0
	v_mul_f32_e32 v48, v48, v44
	v_mul_f32_e32 v49, v49, v45
	v_mul_f32_e32 v50, v50, v46
	v_mul_f32_e32 v51, v51, v47
	v_mul_f32_e32 v52, v52, v48
	v_mul_f32_e32 v53, v53, v49
	v_mul_f32_e32 v54, v54, v50
	v_mul_f32_e32 v55, v55, v51
	v_cvt_pk_bf16_f32 v56, v52, v53
	v_cvt_pk_bf16_f32 v57, v54, v55
	global_store_dwordx2 v35, v[56:57], s[12:13] offset:1088
	v_lshlrev_b32_e32 v44, 16, v106
	v_and_b32_e32 v45, 0xffff0000, v106
	v_lshlrev_b32_e32 v46, 16, v107
	v_and_b32_e32 v47, 0xffff0000, v107
	v_mul_f32_e32 v48, 0xbfb8aa3b, v44
	v_mul_f32_e32 v49, 0xbfb8aa3b, v45
	v_mul_f32_e32 v50, 0xbfb8aa3b, v46
	v_mul_f32_e32 v51, 0xbfb8aa3b, v47
	v_exp_f32_e32 v48, v48
	v_exp_f32_e32 v49, v49
	v_exp_f32_e32 v50, v50
	v_exp_f32_e32 v51, v51
	v_mul_f32_e32 v52, v20, v41
	v_mul_f32_e32 v53, v21, v41
	v_mul_f32_e32 v54, v22, v41
	v_mul_f32_e32 v55, v23, v41
	v_add_f32_e32 v48, 1.0, v48
	v_add_f32_e32 v49, 1.0, v49
	v_add_f32_e32 v50, 1.0, v50
	v_add_f32_e32 v51, 1.0, v51
	v_rcp_f32_e32 v48, v48
	v_rcp_f32_e32 v49, v49
	v_rcp_f32_e32 v50, v50
	v_rcp_f32_e32 v51, v51
	s_nop 0
	v_mul_f32_e32 v48, v48, v44
	v_mul_f32_e32 v49, v49, v45
	v_mul_f32_e32 v50, v50, v46
	v_mul_f32_e32 v51, v51, v47
	v_mul_f32_e32 v52, v52, v48
	v_mul_f32_e32 v53, v53, v49
	v_mul_f32_e32 v54, v54, v50
	v_mul_f32_e32 v55, v55, v51
	v_cvt_pk_bf16_f32 v56, v52, v53
	v_cvt_pk_bf16_f32 v57, v54, v55
	global_store_dwordx2 v35, v[56:57], s[12:13] offset:1120
	v_lshlrev_b32_e32 v44, 16, v108
	v_and_b32_e32 v45, 0xffff0000, v108
	v_lshlrev_b32_e32 v46, 16, v109
	v_and_b32_e32 v47, 0xffff0000, v109
	v_mul_f32_e32 v48, 0xbfb8aa3b, v44
	v_mul_f32_e32 v49, 0xbfb8aa3b, v45
	v_mul_f32_e32 v50, 0xbfb8aa3b, v46
	v_mul_f32_e32 v51, 0xbfb8aa3b, v47
	v_exp_f32_e32 v48, v48
	v_exp_f32_e32 v49, v49
	v_exp_f32_e32 v50, v50
	v_exp_f32_e32 v51, v51
	v_mul_f32_e32 v52, v16, v42
	v_mul_f32_e32 v53, v17, v42
	v_mul_f32_e32 v54, v18, v42
	v_mul_f32_e32 v55, v19, v42
	v_add_f32_e32 v48, 1.0, v48
	v_add_f32_e32 v49, 1.0, v49
	v_add_f32_e32 v50, 1.0, v50
	v_add_f32_e32 v51, 1.0, v51
	v_rcp_f32_e32 v48, v48
	v_rcp_f32_e32 v49, v49
	v_rcp_f32_e32 v50, v50
	v_rcp_f32_e32 v51, v51
	s_nop 0
	v_mul_f32_e32 v48, v48, v44
	v_mul_f32_e32 v49, v49, v45
	v_mul_f32_e32 v50, v50, v46
	v_mul_f32_e32 v51, v51, v47
	v_mul_f32_e32 v52, v52, v48
	v_mul_f32_e32 v53, v53, v49
	v_mul_f32_e32 v54, v54, v50
	v_mul_f32_e32 v55, v55, v51
	v_cvt_pk_bf16_f32 v56, v52, v53
	v_cvt_pk_bf16_f32 v57, v54, v55
	global_store_dwordx2 v36, v[56:57], s[12:13] offset:1024
	v_lshlrev_b32_e32 v44, 16, v110
	v_and_b32_e32 v45, 0xffff0000, v110
	v_lshlrev_b32_e32 v46, 16, v111
	v_and_b32_e32 v47, 0xffff0000, v111
	v_mul_f32_e32 v48, 0xbfb8aa3b, v44
	v_mul_f32_e32 v49, 0xbfb8aa3b, v45
	v_mul_f32_e32 v50, 0xbfb8aa3b, v46
	v_mul_f32_e32 v51, 0xbfb8aa3b, v47
	v_exp_f32_e32 v48, v48
	v_exp_f32_e32 v49, v49
	v_exp_f32_e32 v50, v50
	v_exp_f32_e32 v51, v51
	v_mul_f32_e32 v52, v12, v42
	v_mul_f32_e32 v53, v13, v42
	v_mul_f32_e32 v54, v14, v42
	v_mul_f32_e32 v55, v15, v42
	v_add_f32_e32 v48, 1.0, v48
	v_add_f32_e32 v49, 1.0, v49
	v_add_f32_e32 v50, 1.0, v50
	v_add_f32_e32 v51, 1.0, v51
	v_rcp_f32_e32 v48, v48
	v_rcp_f32_e32 v49, v49
	v_rcp_f32_e32 v50, v50
	v_rcp_f32_e32 v51, v51
	s_nop 0
	v_mul_f32_e32 v48, v48, v44
	v_mul_f32_e32 v49, v49, v45
	v_mul_f32_e32 v50, v50, v46
	v_mul_f32_e32 v51, v51, v47
	v_mul_f32_e32 v52, v52, v48
	v_mul_f32_e32 v53, v53, v49
	v_mul_f32_e32 v54, v54, v50
	v_mul_f32_e32 v55, v55, v51
	v_cvt_pk_bf16_f32 v56, v52, v53
	v_cvt_pk_bf16_f32 v57, v54, v55
	global_store_dwordx2 v36, v[56:57], s[12:13] offset:1056
	v_lshlrev_b32_e32 v44, 16, v112
	v_and_b32_e32 v45, 0xffff0000, v112
	v_lshlrev_b32_e32 v46, 16, v113
	v_and_b32_e32 v47, 0xffff0000, v113
	v_mul_f32_e32 v48, 0xbfb8aa3b, v44
	v_mul_f32_e32 v49, 0xbfb8aa3b, v45
	v_mul_f32_e32 v50, 0xbfb8aa3b, v46
	v_mul_f32_e32 v51, 0xbfb8aa3b, v47
	v_exp_f32_e32 v48, v48
	v_exp_f32_e32 v49, v49
	v_exp_f32_e32 v50, v50
	v_exp_f32_e32 v51, v51
	v_mul_f32_e32 v52, v8, v42
	v_mul_f32_e32 v53, v9, v42
	v_mul_f32_e32 v54, v10, v42
	v_mul_f32_e32 v55, v11, v42
	v_add_f32_e32 v48, 1.0, v48
	v_add_f32_e32 v49, 1.0, v49
	v_add_f32_e32 v50, 1.0, v50
	v_add_f32_e32 v51, 1.0, v51
	v_rcp_f32_e32 v48, v48
	v_rcp_f32_e32 v49, v49
	v_rcp_f32_e32 v50, v50
	v_rcp_f32_e32 v51, v51
	s_nop 0
	v_mul_f32_e32 v48, v48, v44
	v_mul_f32_e32 v49, v49, v45
	v_mul_f32_e32 v50, v50, v46
	v_mul_f32_e32 v51, v51, v47
	v_mul_f32_e32 v52, v52, v48
	v_mul_f32_e32 v53, v53, v49
	v_mul_f32_e32 v54, v54, v50
	v_mul_f32_e32 v55, v55, v51
	v_cvt_pk_bf16_f32 v56, v52, v53
	v_cvt_pk_bf16_f32 v57, v54, v55
	global_store_dwordx2 v36, v[56:57], s[12:13] offset:1088
	v_lshlrev_b32_e32 v44, 16, v114
	v_and_b32_e32 v45, 0xffff0000, v114
	v_lshlrev_b32_e32 v46, 16, v115
	v_and_b32_e32 v47, 0xffff0000, v115
	v_mul_f32_e32 v48, 0xbfb8aa3b, v44
	v_mul_f32_e32 v49, 0xbfb8aa3b, v45
	v_mul_f32_e32 v50, 0xbfb8aa3b, v46
	v_mul_f32_e32 v51, 0xbfb8aa3b, v47
	v_exp_f32_e32 v48, v48
	v_exp_f32_e32 v49, v49
	v_exp_f32_e32 v50, v50
	v_exp_f32_e32 v51, v51
	v_mul_f32_e32 v52, v4, v42
	v_mul_f32_e32 v53, v5, v42
	v_mul_f32_e32 v54, v6, v42
	v_mul_f32_e32 v55, v7, v42
	v_add_f32_e32 v48, 1.0, v48
	v_add_f32_e32 v49, 1.0, v49
	v_add_f32_e32 v50, 1.0, v50
	v_add_f32_e32 v51, 1.0, v51
	v_rcp_f32_e32 v48, v48
	v_rcp_f32_e32 v49, v49
	v_rcp_f32_e32 v50, v50
	v_rcp_f32_e32 v51, v51
	s_nop 0
	v_mul_f32_e32 v48, v48, v44
	v_mul_f32_e32 v49, v49, v45
	v_mul_f32_e32 v50, v50, v46
	v_mul_f32_e32 v51, v51, v47
	v_mul_f32_e32 v52, v52, v48
	v_mul_f32_e32 v53, v53, v49
	v_mul_f32_e32 v54, v54, v50
	v_mul_f32_e32 v55, v55, v51
	v_cvt_pk_bf16_f32 v56, v52, v53
	v_cvt_pk_bf16_f32 v57, v54, v55
	global_store_dwordx2 v36, v[56:57], s[12:13] offset:1120
